# 2-stage GEMM loops: the last k-step no longer waits for its past-the-end loads either
# baseline (speedup 1.0000x reference)
.LBB0_127:
	v_readfirstlane_b32 s6, v136
	s_xor_b32 m0, s20, 1
	s_lshl_b32 m0, m0, 16
	s_add_i32 s6, s6, m0
	v_add3_u32 v178, s10, v149, v150
	v_add_u32_e32 v174, v178, v152
	v_add3_u32 v179, s10, v151, v150
	v_add_u32_e32 v180, v179, v152
	ds_read_b128 v[154:157], v174 offset:32768
	ds_read_b128 v[158:161], v174 offset:34816
	ds_read_b128 v[170:173], v174 offset:36864
	ds_read_b128 v[174:177], v174 offset:38912
	ds_read_b128 v[162:165], v180
	ds_read_b128 v[166:169], v180 offset:2048
	ds_read_b128 v[242:245], v180 offset:4096
	ds_read_b128 v[246:249], v180 offset:6144
	s_mov_b32 m0, s6
	v_lshl_add_u64 v[254:255], v[128:129], 0, s[4:5]
	global_load_lds_dwordx4 v[254:255], off
	s_add_i32 m0, s6, 0x2000
	v_lshl_add_u64 v[254:255], v[130:131], 0, s[4:5]
	global_load_lds_dwordx4 v[254:255], off
	s_waitcnt lgkmcnt(2)
	v_mfma_f32_16x16x32_bf16 v[120:123], v[154:157], v[162:165], v[120:123]
	v_add_u32_e32 v178, v178, v153
	v_add_u32_e32 v179, v179, v153
	v_mfma_f32_16x16x32_bf16 v[104:107], v[154:157], v[166:169], v[104:107]
	v_mfma_f32_16x16x32_bf16 v[116:119], v[158:161], v[162:165], v[116:119]
	v_mfma_f32_16x16x32_bf16 v[100:103], v[158:161], v[166:169], v[100:103]
	s_add_i32 m0, s6, 0x4000
	v_lshl_add_u64 v[254:255], v[132:133], 0, s[4:5]
	global_load_lds_dwordx4 v[254:255], off
	v_mfma_f32_16x16x32_bf16 v[124:127], v[170:173], v[162:165], v[124:127]
	v_mfma_f32_16x16x32_bf16 v[108:111], v[170:173], v[166:169], v[108:111]
	v_mfma_f32_16x16x32_bf16 v[112:115], v[174:177], v[162:165], v[112:115]
	v_mfma_f32_16x16x32_bf16 v[96:99], v[174:177], v[166:169], v[96:99]
	s_add_i32 m0, s6, 0x6000
	v_lshl_add_u64 v[254:255], v[134:135], 0, s[4:5]
	global_load_lds_dwordx4 v[254:255], off
	ds_read_b128 v[162:165], v180 offset:8192
	ds_read_b128 v[166:169], v180 offset:10240
	s_waitcnt lgkmcnt(2)
	v_mfma_f32_16x16x32_bf16 v[88:91], v[154:157], v[242:245], v[88:91]
	v_mfma_f32_16x16x32_bf16 v[72:75], v[154:157], v[246:249], v[72:75]
	v_mfma_f32_16x16x32_bf16 v[84:87], v[158:161], v[242:245], v[84:87]
	v_mfma_f32_16x16x32_bf16 v[68:71], v[158:161], v[246:249], v[68:71]
	s_add_i32 m0, s6, 0x8000
	v_lshl_add_u64 v[254:255], v[138:139], 0, s[4:5]
	global_load_lds_dwordx4 v[254:255], off
	v_mfma_f32_16x16x32_bf16 v[92:95], v[170:173], v[242:245], v[92:95]
	v_mfma_f32_16x16x32_bf16 v[76:79], v[170:173], v[246:249], v[76:79]
	v_mfma_f32_16x16x32_bf16 v[80:83], v[174:177], v[242:245], v[80:83]
	v_mfma_f32_16x16x32_bf16 v[64:67], v[174:177], v[246:249], v[64:67]
	s_add_i32 m0, s6, 0xa000
	v_lshl_add_u64 v[254:255], v[140:141], 0, s[4:5]
	global_load_lds_dwordx4 v[254:255], off
	ds_read_b128 v[242:245], v180 offset:12288
	ds_read_b128 v[246:249], v180 offset:14336
	s_waitcnt lgkmcnt(2)
	v_mfma_f32_16x16x32_bf16 v[56:59], v[154:157], v[162:165], v[56:59]
	v_mfma_f32_16x16x32_bf16 v[40:43], v[154:157], v[166:169], v[40:43]
	v_mfma_f32_16x16x32_bf16 v[52:55], v[158:161], v[162:165], v[52:55]
	v_mfma_f32_16x16x32_bf16 v[36:39], v[158:161], v[166:169], v[36:39]
	s_add_i32 m0, s6, 0xc000
	v_lshl_add_u64 v[254:255], v[142:143], 0, s[4:5]
	global_load_lds_dwordx4 v[254:255], off
	v_mfma_f32_16x16x32_bf16 v[60:63], v[170:173], v[162:165], v[60:63]
	v_mfma_f32_16x16x32_bf16 v[44:47], v[170:173], v[166:169], v[44:47]
	v_mfma_f32_16x16x32_bf16 v[48:51], v[174:177], v[162:165], v[48:51]
	v_mfma_f32_16x16x32_bf16 v[32:35], v[174:177], v[166:169], v[32:35]
	s_add_i32 m0, s6, 0xe000
	v_lshl_add_u64 v[254:255], v[144:145], 0, s[4:5]
	global_load_lds_dwordx4 v[254:255], off
	s_add_u32 s4, s4, 0x80
	s_addc_u32 s5, s5, 0
	s_add_i32 s3, s3, 1
	s_cmpk_lg_i32 s4, 0x800
	ds_read_b128 v[162:165], v179
	ds_read_b128 v[166:169], v179 offset:2048
	s_waitcnt lgkmcnt(2)
	v_mfma_f32_16x16x32_bf16 v[24:27], v[154:157], v[242:245], v[24:27]
	v_mfma_f32_16x16x32_bf16 v[4:7], v[154:157], v[246:249], v[4:7]
	ds_read_b128 v[154:157], v178 offset:32768
	v_mfma_f32_16x16x32_bf16 v[20:23], v[158:161], v[242:245], v[20:23]
	v_mfma_f32_16x16x32_bf16 v[0:3], v[158:161], v[246:249], v[0:3]
	ds_read_b128 v[158:161], v178 offset:34816
	v_mfma_f32_16x16x32_bf16 v[28:31], v[170:173], v[242:245], v[28:31]
	v_mfma_f32_16x16x32_bf16 v[8:11], v[170:173], v[246:249], v[8:11]
	ds_read_b128 v[170:173], v178 offset:36864
	v_mfma_f32_16x16x32_bf16 v[16:19], v[174:177], v[242:245], v[16:19]
	v_mfma_f32_16x16x32_bf16 v[12:15], v[174:177], v[246:249], v[12:15]
	ds_read_b128 v[174:177], v178 offset:38912
	ds_read_b128 v[242:245], v179 offset:4096
	ds_read_b128 v[246:249], v179 offset:6144
	s_waitcnt lgkmcnt(2)
	v_mfma_f32_16x16x32_bf16 v[120:123], v[154:157], v[162:165], v[120:123]
	v_mfma_f32_16x16x32_bf16 v[104:107], v[154:157], v[166:169], v[104:107]
	v_mfma_f32_16x16x32_bf16 v[116:119], v[158:161], v[162:165], v[116:119]
	v_mfma_f32_16x16x32_bf16 v[100:103], v[158:161], v[166:169], v[100:103]
	v_mfma_f32_16x16x32_bf16 v[124:127], v[170:173], v[162:165], v[124:127]
	v_mfma_f32_16x16x32_bf16 v[108:111], v[170:173], v[166:169], v[108:111]
	v_mfma_f32_16x16x32_bf16 v[112:115], v[174:177], v[162:165], v[112:115]
	v_mfma_f32_16x16x32_bf16 v[96:99], v[174:177], v[166:169], v[96:99]
	ds_read_b128 v[162:165], v179 offset:8192
	ds_read_b128 v[166:169], v179 offset:10240
	s_waitcnt lgkmcnt(2)
	v_mfma_f32_16x16x32_bf16 v[88:91], v[154:157], v[242:245], v[88:91]
	v_mfma_f32_16x16x32_bf16 v[72:75], v[154:157], v[246:249], v[72:75]
	v_mfma_f32_16x16x32_bf16 v[84:87], v[158:161], v[242:245], v[84:87]
	v_mfma_f32_16x16x32_bf16 v[68:71], v[158:161], v[246:249], v[68:71]
	v_mfma_f32_16x16x32_bf16 v[92:95], v[170:173], v[242:245], v[92:95]
	v_mfma_f32_16x16x32_bf16 v[76:79], v[170:173], v[246:249], v[76:79]
	v_mfma_f32_16x16x32_bf16 v[80:83], v[174:177], v[242:245], v[80:83]
	v_mfma_f32_16x16x32_bf16 v[64:67], v[174:177], v[246:249], v[64:67]
	ds_read_b128 v[242:245], v179 offset:12288
	ds_read_b128 v[246:249], v179 offset:14336
	s_waitcnt lgkmcnt(2)
	v_mfma_f32_16x16x32_bf16 v[56:59], v[154:157], v[162:165], v[56:59]
	v_mfma_f32_16x16x32_bf16 v[40:43], v[154:157], v[166:169], v[40:43]
	v_mfma_f32_16x16x32_bf16 v[52:55], v[158:161], v[162:165], v[52:55]
	v_mfma_f32_16x16x32_bf16 v[36:39], v[158:161], v[166:169], v[36:39]
	v_mfma_f32_16x16x32_bf16 v[60:63], v[170:173], v[162:165], v[60:63]
	v_mfma_f32_16x16x32_bf16 v[44:47], v[170:173], v[166:169], v[44:47]
	v_mfma_f32_16x16x32_bf16 v[48:51], v[174:177], v[162:165], v[48:51]
	v_mfma_f32_16x16x32_bf16 v[32:35], v[174:177], v[166:169], v[32:35]
	s_cbranch_scc0 .Lg2l_gemm9
	s_waitcnt vmcnt(0) lgkmcnt(0)
	s_branch .Lg2j_gemm9

.Lg2j_gemm9:
	v_mfma_f32_16x16x32_bf16 v[24:27], v[154:157], v[242:245], v[24:27]
	s_barrier
	v_mfma_f32_16x16x32_bf16 v[4:7], v[154:157], v[246:249], v[4:7]
	v_mfma_f32_16x16x32_bf16 v[20:23], v[158:161], v[242:245], v[20:23]
	v_mfma_f32_16x16x32_bf16 v[0:3], v[158:161], v[246:249], v[0:3]
	v_mfma_f32_16x16x32_bf16 v[28:31], v[170:173], v[242:245], v[28:31]
	v_mfma_f32_16x16x32_bf16 v[8:11], v[170:173], v[246:249], v[8:11]
	v_mfma_f32_16x16x32_bf16 v[16:19], v[174:177], v[242:245], v[16:19]
	v_mfma_f32_16x16x32_bf16 v[12:15], v[174:177], v[246:249], v[12:15]
	s_cbranch_scc0 .LBB0_132

.LBB0_389:
	v_readfirstlane_b32 s6, v150
	s_xor_b32 m0, s74, 1
	s_lshl_b32 m0, m0, 16
	s_add_i32 s6, s6, m0
	v_add3_u32 v168, s67, v151, v152
	v_add3_u32 v185, s67, v153, v152
	v_add_u32_e32 v170, v168, v154
	v_add_u32_e32 v186, v185, v154
	ds_read_b128 v[128:131], v170 offset:32768
	ds_read_b128 v[160:163], v170 offset:34816
	ds_read_b128 v[164:167], v170 offset:36864
	ds_read_b128 v[170:173], v170 offset:38912
	ds_read_b128 v[156:159], v186
	ds_read_b128 v[250:253], v186 offset:2048
	ds_read_b128 v[242:245], v186 offset:4096
	ds_read_b128 v[246:249], v186 offset:6144
	s_mov_b32 m0, s6
	v_lshl_add_u64 v[254:255], v[132:133], 0, s[2:3]
	global_load_lds_dwordx4 v[254:255], off
	s_add_i32 m0, s6, 0x2000
	v_lshl_add_u64 v[254:255], v[134:135], 0, s[2:3]
	global_load_lds_dwordx4 v[254:255], off
	s_waitcnt lgkmcnt(2)
	v_mfma_f32_16x16x32_bf16 v[124:127], v[128:131], v[156:159], v[124:127]
	v_add_u32_e32 v241, v168, v155
	v_add_u32_e32 v168, v185, v155
	v_mfma_f32_16x16x32_bf16 v[108:111], v[128:131], v[250:253], v[108:111]
	v_mfma_f32_16x16x32_bf16 v[120:123], v[160:163], v[156:159], v[120:123]
	v_mfma_f32_16x16x32_bf16 v[104:107], v[160:163], v[250:253], v[104:107]
	s_add_i32 m0, s6, 0x4000
	v_lshl_add_u64 v[254:255], v[136:137], 0, s[2:3]
	global_load_lds_dwordx4 v[254:255], off
	v_mfma_f32_16x16x32_bf16 v[116:119], v[164:167], v[156:159], v[116:119]
	v_mfma_f32_16x16x32_bf16 v[100:103], v[164:167], v[250:253], v[100:103]
	v_mfma_f32_16x16x32_bf16 v[112:115], v[170:173], v[156:159], v[112:115]
	v_mfma_f32_16x16x32_bf16 v[96:99], v[170:173], v[250:253], v[96:99]
	s_add_i32 m0, s6, 0x6000
	v_lshl_add_u64 v[254:255], v[138:139], 0, s[2:3]
	global_load_lds_dwordx4 v[254:255], off
	ds_read_b128 v[156:159], v186 offset:8192
	ds_read_b128 v[250:253], v186 offset:10240
	s_waitcnt lgkmcnt(2)
	v_mfma_f32_16x16x32_bf16 v[92:95], v[128:131], v[242:245], v[92:95]
	v_mfma_f32_16x16x32_bf16 v[76:79], v[128:131], v[246:249], v[76:79]
	v_mfma_f32_16x16x32_bf16 v[88:91], v[160:163], v[242:245], v[88:91]
	v_mfma_f32_16x16x32_bf16 v[72:75], v[160:163], v[246:249], v[72:75]
	s_add_i32 m0, s6, 0x8000
	v_lshl_add_u64 v[254:255], v[140:141], 0, s[2:3]
	global_load_lds_dwordx4 v[254:255], off
	v_mfma_f32_16x16x32_bf16 v[84:87], v[164:167], v[242:245], v[84:87]
	v_mfma_f32_16x16x32_bf16 v[68:71], v[164:167], v[246:249], v[68:71]
	v_mfma_f32_16x16x32_bf16 v[80:83], v[170:173], v[242:245], v[80:83]
	v_mfma_f32_16x16x32_bf16 v[64:67], v[170:173], v[246:249], v[64:67]
	s_add_i32 m0, s6, 0xa000
	v_lshl_add_u64 v[254:255], v[142:143], 0, s[2:3]
	global_load_lds_dwordx4 v[254:255], off
	ds_read_b128 v[242:245], v186 offset:12288
	ds_read_b128 v[246:249], v186 offset:14336
	s_waitcnt lgkmcnt(2)
	v_mfma_f32_16x16x32_bf16 v[60:63], v[128:131], v[156:159], v[60:63]
	v_mfma_f32_16x16x32_bf16 v[44:47], v[128:131], v[250:253], v[44:47]
	v_mfma_f32_16x16x32_bf16 v[56:59], v[160:163], v[156:159], v[56:59]
	v_mfma_f32_16x16x32_bf16 v[40:43], v[160:163], v[250:253], v[40:43]
	s_add_i32 m0, s6, 0xc000
	v_lshl_add_u64 v[254:255], v[144:145], 0, s[2:3]
	global_load_lds_dwordx4 v[254:255], off
	v_mfma_f32_16x16x32_bf16 v[52:55], v[164:167], v[156:159], v[52:55]
	v_mfma_f32_16x16x32_bf16 v[36:39], v[164:167], v[250:253], v[36:39]
	v_mfma_f32_16x16x32_bf16 v[48:51], v[170:173], v[156:159], v[48:51]
	v_mfma_f32_16x16x32_bf16 v[32:35], v[170:173], v[250:253], v[32:35]
	s_add_i32 m0, s6, 0xe000
	v_lshl_add_u64 v[254:255], v[146:147], 0, s[2:3]
	global_load_lds_dwordx4 v[254:255], off
	s_add_u32 s2, s2, 0x80
	s_addc_u32 s3, s3, 0
	s_add_i32 s66, s66, 1
	s_cmpk_lg_i32 s2, 0x200
	ds_read_b128 v[156:159], v168
	ds_read_b128 v[250:253], v168 offset:2048
	s_waitcnt lgkmcnt(2)
	v_mfma_f32_16x16x32_bf16 v[28:31], v[128:131], v[242:245], v[28:31]
	v_mfma_f32_16x16x32_bf16 v[12:15], v[128:131], v[246:249], v[12:15]
	ds_read_b128 v[128:131], v241 offset:32768
	v_mfma_f32_16x16x32_bf16 v[24:27], v[160:163], v[242:245], v[24:27]
	v_mfma_f32_16x16x32_bf16 v[8:11], v[160:163], v[246:249], v[8:11]
	ds_read_b128 v[160:163], v241 offset:34816
	v_mfma_f32_16x16x32_bf16 v[20:23], v[164:167], v[242:245], v[20:23]
	v_mfma_f32_16x16x32_bf16 v[0:3], v[164:167], v[246:249], v[0:3]
	ds_read_b128 v[164:167], v241 offset:36864
	v_mfma_f32_16x16x32_bf16 v[16:19], v[170:173], v[242:245], v[16:19]
	v_mfma_f32_16x16x32_bf16 v[4:7], v[170:173], v[246:249], v[4:7]
	ds_read_b128 v[170:173], v241 offset:38912
	ds_read_b128 v[242:245], v168 offset:4096
	ds_read_b128 v[246:249], v168 offset:6144
	s_waitcnt lgkmcnt(2)
	v_mfma_f32_16x16x32_bf16 v[124:127], v[128:131], v[156:159], v[124:127]
	v_mfma_f32_16x16x32_bf16 v[108:111], v[128:131], v[250:253], v[108:111]
	v_mfma_f32_16x16x32_bf16 v[120:123], v[160:163], v[156:159], v[120:123]
	v_mfma_f32_16x16x32_bf16 v[104:107], v[160:163], v[250:253], v[104:107]
	v_mfma_f32_16x16x32_bf16 v[116:119], v[164:167], v[156:159], v[116:119]
	v_mfma_f32_16x16x32_bf16 v[100:103], v[164:167], v[250:253], v[100:103]
	v_mfma_f32_16x16x32_bf16 v[112:115], v[170:173], v[156:159], v[112:115]
	v_mfma_f32_16x16x32_bf16 v[96:99], v[170:173], v[250:253], v[96:99]
	ds_read_b128 v[156:159], v168 offset:8192
	ds_read_b128 v[250:253], v168 offset:10240
	s_waitcnt lgkmcnt(2)
	v_mfma_f32_16x16x32_bf16 v[92:95], v[128:131], v[242:245], v[92:95]
	v_mfma_f32_16x16x32_bf16 v[76:79], v[128:131], v[246:249], v[76:79]
	v_mfma_f32_16x16x32_bf16 v[88:91], v[160:163], v[242:245], v[88:91]
	v_mfma_f32_16x16x32_bf16 v[72:75], v[160:163], v[246:249], v[72:75]
	v_mfma_f32_16x16x32_bf16 v[84:87], v[164:167], v[242:245], v[84:87]
	v_mfma_f32_16x16x32_bf16 v[68:71], v[164:167], v[246:249], v[68:71]
	v_mfma_f32_16x16x32_bf16 v[80:83], v[170:173], v[242:245], v[80:83]
	v_mfma_f32_16x16x32_bf16 v[64:67], v[170:173], v[246:249], v[64:67]
	ds_read_b128 v[242:245], v168 offset:12288
	ds_read_b128 v[246:249], v168 offset:14336
	s_waitcnt lgkmcnt(2)
	v_mfma_f32_16x16x32_bf16 v[60:63], v[128:131], v[156:159], v[60:63]
	v_mfma_f32_16x16x32_bf16 v[44:47], v[128:131], v[250:253], v[44:47]
	v_mfma_f32_16x16x32_bf16 v[56:59], v[160:163], v[156:159], v[56:59]
	v_mfma_f32_16x16x32_bf16 v[40:43], v[160:163], v[250:253], v[40:43]
	v_mfma_f32_16x16x32_bf16 v[52:55], v[164:167], v[156:159], v[52:55]
	v_mfma_f32_16x16x32_bf16 v[36:39], v[164:167], v[250:253], v[36:39]
	v_mfma_f32_16x16x32_bf16 v[48:51], v[170:173], v[156:159], v[48:51]
	v_mfma_f32_16x16x32_bf16 v[32:35], v[170:173], v[250:253], v[32:35]
	s_cbranch_scc0 .Lg2l_gemm8
	s_waitcnt vmcnt(0) lgkmcnt(0)
	s_branch .Lg2j_gemm8

.Lg2j_gemm8:
	v_mfma_f32_16x16x32_bf16 v[28:31], v[128:131], v[242:245], v[28:31]
	s_barrier
	v_mfma_f32_16x16x32_bf16 v[12:15], v[128:131], v[246:249], v[12:15]
	v_mfma_f32_16x16x32_bf16 v[24:27], v[160:163], v[242:245], v[24:27]
	v_mfma_f32_16x16x32_bf16 v[8:11], v[160:163], v[246:249], v[8:11]
	v_mfma_f32_16x16x32_bf16 v[20:23], v[164:167], v[242:245], v[20:23]
	v_mfma_f32_16x16x32_bf16 v[0:3], v[164:167], v[246:249], v[0:3]
	v_mfma_f32_16x16x32_bf16 v[16:19], v[170:173], v[242:245], v[16:19]
	v_mfma_f32_16x16x32_bf16 v[4:7], v[170:173], v[246:249], v[4:7]
	s_cbranch_scc0 .LBB0_394

.LBB0_765:
	v_readfirstlane_b32 s18, v146
	s_xor_b32 m0, s34, 1
	s_lshl_b32 m0, m0, 16
	s_add_i32 s18, s18, m0
	v_add3_u32 v128, s31, v147, v148
	v_add_u32_e32 v172, v128, v150
	v_add3_u32 v176, s31, v149, v148
	v_add_u32_e32 v177, v176, v150
	ds_read_b128 v[152:155], v172 offset:32768
	ds_read_b128 v[156:159], v172 offset:34816
	ds_read_b128 v[168:171], v172 offset:36864
	ds_read_b128 v[172:175], v172 offset:38912
	ds_read_b128 v[160:163], v177
	ds_read_b128 v[164:167], v177 offset:2048
	ds_read_b128 v[242:245], v177 offset:4096
	ds_read_b128 v[246:249], v177 offset:6144
	s_mov_b32 m0, s18
	v_lshl_add_u64 v[254:255], v[130:131], 0, s[16:17]
	global_load_lds_dwordx4 v[254:255], off
	s_add_i32 m0, s18, 0x2000
	v_lshl_add_u64 v[254:255], v[132:133], 0, s[16:17]
	global_load_lds_dwordx4 v[254:255], off
	s_waitcnt lgkmcnt(2)
	v_mfma_f32_16x16x32_bf16 v[124:127], v[152:155], v[160:163], v[124:127]
	v_add_u32_e32 v128, v128, v151
	v_add_u32_e32 v176, v176, v151
	v_mfma_f32_16x16x32_bf16 v[108:111], v[152:155], v[164:167], v[108:111]
	v_mfma_f32_16x16x32_bf16 v[120:123], v[156:159], v[160:163], v[120:123]
	v_mfma_f32_16x16x32_bf16 v[104:107], v[156:159], v[164:167], v[104:107]
	s_add_i32 m0, s18, 0x4000
	v_lshl_add_u64 v[254:255], v[134:135], 0, s[16:17]
	global_load_lds_dwordx4 v[254:255], off
	v_mfma_f32_16x16x32_bf16 v[116:119], v[168:171], v[160:163], v[116:119]
	v_mfma_f32_16x16x32_bf16 v[100:103], v[168:171], v[164:167], v[100:103]
	v_mfma_f32_16x16x32_bf16 v[112:115], v[172:175], v[160:163], v[112:115]
	v_mfma_f32_16x16x32_bf16 v[96:99], v[172:175], v[164:167], v[96:99]
	s_add_i32 m0, s18, 0x6000
	v_lshl_add_u64 v[254:255], v[136:137], 0, s[16:17]
	global_load_lds_dwordx4 v[254:255], off
	ds_read_b128 v[160:163], v177 offset:8192
	ds_read_b128 v[164:167], v177 offset:10240
	s_waitcnt lgkmcnt(2)
	v_mfma_f32_16x16x32_bf16 v[92:95], v[152:155], v[242:245], v[92:95]
	v_mfma_f32_16x16x32_bf16 v[76:79], v[152:155], v[246:249], v[76:79]
	v_mfma_f32_16x16x32_bf16 v[88:91], v[156:159], v[242:245], v[88:91]
	v_mfma_f32_16x16x32_bf16 v[72:75], v[156:159], v[246:249], v[72:75]
	s_add_i32 m0, s18, 0x8000
	v_lshl_add_u64 v[254:255], v[138:139], 0, s[16:17]
	global_load_lds_dwordx4 v[254:255], off
	v_mfma_f32_16x16x32_bf16 v[84:87], v[168:171], v[242:245], v[84:87]
	v_mfma_f32_16x16x32_bf16 v[68:71], v[168:171], v[246:249], v[68:71]
	v_mfma_f32_16x16x32_bf16 v[80:83], v[172:175], v[242:245], v[80:83]
	v_mfma_f32_16x16x32_bf16 v[64:67], v[172:175], v[246:249], v[64:67]
	s_add_i32 m0, s18, 0xa000
	v_lshl_add_u64 v[254:255], v[140:141], 0, s[16:17]
	global_load_lds_dwordx4 v[254:255], off
	ds_read_b128 v[242:245], v177 offset:12288
	ds_read_b128 v[246:249], v177 offset:14336
	s_waitcnt lgkmcnt(2)
	v_mfma_f32_16x16x32_bf16 v[60:63], v[152:155], v[160:163], v[60:63]
	v_mfma_f32_16x16x32_bf16 v[44:47], v[152:155], v[164:167], v[44:47]
	v_mfma_f32_16x16x32_bf16 v[56:59], v[156:159], v[160:163], v[56:59]
	v_mfma_f32_16x16x32_bf16 v[40:43], v[156:159], v[164:167], v[40:43]
	s_add_i32 m0, s18, 0xc000
	v_lshl_add_u64 v[254:255], v[142:143], 0, s[16:17]
	global_load_lds_dwordx4 v[254:255], off
	v_mfma_f32_16x16x32_bf16 v[52:55], v[168:171], v[160:163], v[52:55]
	v_mfma_f32_16x16x32_bf16 v[36:39], v[168:171], v[164:167], v[36:39]
	v_mfma_f32_16x16x32_bf16 v[48:51], v[172:175], v[160:163], v[48:51]
	v_mfma_f32_16x16x32_bf16 v[32:35], v[172:175], v[164:167], v[32:35]
	s_add_i32 m0, s18, 0xe000
	v_lshl_add_u64 v[254:255], v[144:145], 0, s[16:17]
	global_load_lds_dwordx4 v[254:255], off
	s_add_u32 s16, s16, 0x80
	s_addc_u32 s17, s17, 0
	s_add_i32 s15, s15, 1
	s_cmpk_lg_i32 s16, 0x800
	ds_read_b128 v[160:163], v176
	ds_read_b128 v[164:167], v176 offset:2048
	s_waitcnt lgkmcnt(2)
	v_mfma_f32_16x16x32_bf16 v[28:31], v[152:155], v[242:245], v[28:31]
	v_mfma_f32_16x16x32_bf16 v[8:11], v[152:155], v[246:249], v[8:11]
	ds_read_b128 v[152:155], v128 offset:32768
	v_mfma_f32_16x16x32_bf16 v[20:23], v[156:159], v[242:245], v[20:23]
	v_mfma_f32_16x16x32_bf16 v[4:7], v[156:159], v[246:249], v[4:7]
	ds_read_b128 v[156:159], v128 offset:34816
	v_mfma_f32_16x16x32_bf16 v[16:19], v[168:171], v[242:245], v[16:19]
	v_mfma_f32_16x16x32_bf16 v[0:3], v[168:171], v[246:249], v[0:3]
	ds_read_b128 v[168:171], v128 offset:36864
	v_mfma_f32_16x16x32_bf16 v[12:15], v[172:175], v[242:245], v[12:15]
	v_mfma_f32_16x16x32_bf16 v[24:27], v[172:175], v[246:249], v[24:27]
	ds_read_b128 v[172:175], v128 offset:38912
	ds_read_b128 v[242:245], v176 offset:4096
	ds_read_b128 v[246:249], v176 offset:6144
	s_waitcnt lgkmcnt(2)
	v_mfma_f32_16x16x32_bf16 v[124:127], v[152:155], v[160:163], v[124:127]
	v_mfma_f32_16x16x32_bf16 v[108:111], v[152:155], v[164:167], v[108:111]
	v_mfma_f32_16x16x32_bf16 v[120:123], v[156:159], v[160:163], v[120:123]
	v_mfma_f32_16x16x32_bf16 v[104:107], v[156:159], v[164:167], v[104:107]
	v_mfma_f32_16x16x32_bf16 v[116:119], v[168:171], v[160:163], v[116:119]
	v_mfma_f32_16x16x32_bf16 v[100:103], v[168:171], v[164:167], v[100:103]
	v_mfma_f32_16x16x32_bf16 v[112:115], v[172:175], v[160:163], v[112:115]
	v_mfma_f32_16x16x32_bf16 v[96:99], v[172:175], v[164:167], v[96:99]
	ds_read_b128 v[160:163], v176 offset:8192
	ds_read_b128 v[164:167], v176 offset:10240
	s_waitcnt lgkmcnt(2)
	v_mfma_f32_16x16x32_bf16 v[92:95], v[152:155], v[242:245], v[92:95]
	v_mfma_f32_16x16x32_bf16 v[76:79], v[152:155], v[246:249], v[76:79]
	v_mfma_f32_16x16x32_bf16 v[88:91], v[156:159], v[242:245], v[88:91]
	v_mfma_f32_16x16x32_bf16 v[72:75], v[156:159], v[246:249], v[72:75]
	v_mfma_f32_16x16x32_bf16 v[84:87], v[168:171], v[242:245], v[84:87]
	v_mfma_f32_16x16x32_bf16 v[68:71], v[168:171], v[246:249], v[68:71]
	v_mfma_f32_16x16x32_bf16 v[80:83], v[172:175], v[242:245], v[80:83]
	v_mfma_f32_16x16x32_bf16 v[64:67], v[172:175], v[246:249], v[64:67]
	ds_read_b128 v[242:245], v176 offset:12288
	ds_read_b128 v[246:249], v176 offset:14336
	s_waitcnt lgkmcnt(2)
	v_mfma_f32_16x16x32_bf16 v[60:63], v[152:155], v[160:163], v[60:63]
	v_mfma_f32_16x16x32_bf16 v[44:47], v[152:155], v[164:167], v[44:47]
	v_mfma_f32_16x16x32_bf16 v[56:59], v[156:159], v[160:163], v[56:59]
	v_mfma_f32_16x16x32_bf16 v[40:43], v[156:159], v[164:167], v[40:43]
	v_mfma_f32_16x16x32_bf16 v[52:55], v[168:171], v[160:163], v[52:55]
	v_mfma_f32_16x16x32_bf16 v[36:39], v[168:171], v[164:167], v[36:39]
	v_mfma_f32_16x16x32_bf16 v[48:51], v[172:175], v[160:163], v[48:51]
	v_mfma_f32_16x16x32_bf16 v[32:35], v[172:175], v[164:167], v[32:35]
	s_cbranch_scc0 .Lg2l_gemm5
	s_waitcnt vmcnt(0) lgkmcnt(0)
	s_branch .Lg2j_gemm5

.Lg2j_gemm5:
	v_mfma_f32_16x16x32_bf16 v[28:31], v[152:155], v[242:245], v[28:31]
	s_barrier
	v_mfma_f32_16x16x32_bf16 v[8:11], v[152:155], v[246:249], v[8:11]
	v_mfma_f32_16x16x32_bf16 v[20:23], v[156:159], v[242:245], v[20:23]
	v_mfma_f32_16x16x32_bf16 v[4:7], v[156:159], v[246:249], v[4:7]
	v_mfma_f32_16x16x32_bf16 v[16:19], v[168:171], v[242:245], v[16:19]
	v_mfma_f32_16x16x32_bf16 v[0:3], v[168:171], v[246:249], v[0:3]
	v_mfma_f32_16x16x32_bf16 v[12:15], v[172:175], v[242:245], v[12:15]
	v_mfma_f32_16x16x32_bf16 v[24:27], v[172:175], v[246:249], v[24:27]
	s_cbranch_scc0 .LBB0_762

.LBB0_1155:
	v_readfirstlane_b32 s6, v150
	s_xor_b32 m0, s76, 1
	s_lshl_b32 m0, m0, 16
	s_add_i32 s6, s6, m0
	v_add3_u32 v168, s75, v151, v152
	v_add_u32_e32 v170, v168, v154
	v_add3_u32 v186, s75, v153, v152
	v_add_u32_e32 v187, v186, v154
	ds_read_b128 v[128:131], v170 offset:32768
	ds_read_b128 v[160:163], v170 offset:34816
	ds_read_b128 v[164:167], v170 offset:36864
	ds_read_b128 v[170:173], v170 offset:38912
	ds_read_b128 v[156:159], v187
	ds_read_b128 v[250:253], v187 offset:2048
	ds_read_b128 v[242:245], v187 offset:4096
	ds_read_b128 v[246:249], v187 offset:6144
	s_mov_b32 m0, s6
	v_lshl_add_u64 v[254:255], v[132:133], 0, s[2:3]
	global_load_lds_dwordx4 v[254:255], off
	s_add_i32 m0, s6, 0x2000
	v_lshl_add_u64 v[254:255], v[134:135], 0, s[2:3]
	global_load_lds_dwordx4 v[254:255], off
	s_waitcnt lgkmcnt(2)
	v_mfma_f32_16x16x32_bf16 v[124:127], v[128:131], v[156:159], v[124:127]
	v_add_u32_e32 v241, v168, v155
	v_add_u32_e32 v168, v186, v155
	v_mfma_f32_16x16x32_bf16 v[108:111], v[128:131], v[250:253], v[108:111]
	v_mfma_f32_16x16x32_bf16 v[120:123], v[160:163], v[156:159], v[120:123]
	v_mfma_f32_16x16x32_bf16 v[104:107], v[160:163], v[250:253], v[104:107]
	s_add_i32 m0, s6, 0x4000
	v_lshl_add_u64 v[254:255], v[136:137], 0, s[2:3]
	global_load_lds_dwordx4 v[254:255], off
	v_mfma_f32_16x16x32_bf16 v[116:119], v[164:167], v[156:159], v[116:119]
	v_mfma_f32_16x16x32_bf16 v[100:103], v[164:167], v[250:253], v[100:103]
	v_mfma_f32_16x16x32_bf16 v[112:115], v[170:173], v[156:159], v[112:115]
	v_mfma_f32_16x16x32_bf16 v[96:99], v[170:173], v[250:253], v[96:99]
	s_add_i32 m0, s6, 0x6000
	v_lshl_add_u64 v[254:255], v[138:139], 0, s[2:3]
	global_load_lds_dwordx4 v[254:255], off
	ds_read_b128 v[156:159], v187 offset:8192
	ds_read_b128 v[250:253], v187 offset:10240
	s_waitcnt lgkmcnt(2)
	v_mfma_f32_16x16x32_bf16 v[92:95], v[128:131], v[242:245], v[92:95]
	v_mfma_f32_16x16x32_bf16 v[76:79], v[128:131], v[246:249], v[76:79]
	v_mfma_f32_16x16x32_bf16 v[88:91], v[160:163], v[242:245], v[88:91]
	v_mfma_f32_16x16x32_bf16 v[72:75], v[160:163], v[246:249], v[72:75]
	s_add_i32 m0, s6, 0x8000
	v_lshl_add_u64 v[254:255], v[140:141], 0, s[2:3]
	global_load_lds_dwordx4 v[254:255], off
	v_mfma_f32_16x16x32_bf16 v[84:87], v[164:167], v[242:245], v[84:87]
	v_mfma_f32_16x16x32_bf16 v[68:71], v[164:167], v[246:249], v[68:71]
	v_mfma_f32_16x16x32_bf16 v[80:83], v[170:173], v[242:245], v[80:83]
	v_mfma_f32_16x16x32_bf16 v[64:67], v[170:173], v[246:249], v[64:67]
	s_add_i32 m0, s6, 0xa000
	v_lshl_add_u64 v[254:255], v[142:143], 0, s[2:3]
	global_load_lds_dwordx4 v[254:255], off
	ds_read_b128 v[242:245], v187 offset:12288
	ds_read_b128 v[246:249], v187 offset:14336
	s_waitcnt lgkmcnt(2)
	v_mfma_f32_16x16x32_bf16 v[60:63], v[128:131], v[156:159], v[60:63]
	v_mfma_f32_16x16x32_bf16 v[44:47], v[128:131], v[250:253], v[44:47]
	v_mfma_f32_16x16x32_bf16 v[56:59], v[160:163], v[156:159], v[56:59]
	v_mfma_f32_16x16x32_bf16 v[40:43], v[160:163], v[250:253], v[40:43]
	s_add_i32 m0, s6, 0xc000
	v_lshl_add_u64 v[254:255], v[144:145], 0, s[2:3]
	global_load_lds_dwordx4 v[254:255], off
	v_mfma_f32_16x16x32_bf16 v[52:55], v[164:167], v[156:159], v[52:55]
	v_mfma_f32_16x16x32_bf16 v[36:39], v[164:167], v[250:253], v[36:39]
	v_mfma_f32_16x16x32_bf16 v[48:51], v[170:173], v[156:159], v[48:51]
	v_mfma_f32_16x16x32_bf16 v[32:35], v[170:173], v[250:253], v[32:35]
	s_add_i32 m0, s6, 0xe000
	v_lshl_add_u64 v[254:255], v[146:147], 0, s[2:3]
	global_load_lds_dwordx4 v[254:255], off
	s_add_u32 s2, s2, 0x80
	s_addc_u32 s3, s3, 0
	s_add_i32 s74, s74, 1
	s_cmpk_lg_i32 s2, 0x200
	ds_read_b128 v[156:159], v168
	ds_read_b128 v[250:253], v168 offset:2048
	s_waitcnt lgkmcnt(2)
	v_mfma_f32_16x16x32_bf16 v[28:31], v[128:131], v[242:245], v[28:31]
	v_mfma_f32_16x16x32_bf16 v[12:15], v[128:131], v[246:249], v[12:15]
	ds_read_b128 v[128:131], v241 offset:32768
	v_mfma_f32_16x16x32_bf16 v[24:27], v[160:163], v[242:245], v[24:27]
	v_mfma_f32_16x16x32_bf16 v[8:11], v[160:163], v[246:249], v[8:11]
	ds_read_b128 v[160:163], v241 offset:34816
	v_mfma_f32_16x16x32_bf16 v[20:23], v[164:167], v[242:245], v[20:23]
	v_mfma_f32_16x16x32_bf16 v[0:3], v[164:167], v[246:249], v[0:3]
	ds_read_b128 v[164:167], v241 offset:36864
	v_mfma_f32_16x16x32_bf16 v[16:19], v[170:173], v[242:245], v[16:19]
	v_mfma_f32_16x16x32_bf16 v[4:7], v[170:173], v[246:249], v[4:7]
	ds_read_b128 v[170:173], v241 offset:38912
	ds_read_b128 v[242:245], v168 offset:4096
	ds_read_b128 v[246:249], v168 offset:6144
	s_waitcnt lgkmcnt(2)
	v_mfma_f32_16x16x32_bf16 v[124:127], v[128:131], v[156:159], v[124:127]
	v_mfma_f32_16x16x32_bf16 v[108:111], v[128:131], v[250:253], v[108:111]
	v_mfma_f32_16x16x32_bf16 v[120:123], v[160:163], v[156:159], v[120:123]
	v_mfma_f32_16x16x32_bf16 v[104:107], v[160:163], v[250:253], v[104:107]
	v_mfma_f32_16x16x32_bf16 v[116:119], v[164:167], v[156:159], v[116:119]
	v_mfma_f32_16x16x32_bf16 v[100:103], v[164:167], v[250:253], v[100:103]
	v_mfma_f32_16x16x32_bf16 v[112:115], v[170:173], v[156:159], v[112:115]
	v_mfma_f32_16x16x32_bf16 v[96:99], v[170:173], v[250:253], v[96:99]
	ds_read_b128 v[156:159], v168 offset:8192
	ds_read_b128 v[250:253], v168 offset:10240
	s_waitcnt lgkmcnt(2)
	v_mfma_f32_16x16x32_bf16 v[92:95], v[128:131], v[242:245], v[92:95]
	v_mfma_f32_16x16x32_bf16 v[76:79], v[128:131], v[246:249], v[76:79]
	v_mfma_f32_16x16x32_bf16 v[88:91], v[160:163], v[242:245], v[88:91]
	v_mfma_f32_16x16x32_bf16 v[72:75], v[160:163], v[246:249], v[72:75]
	v_mfma_f32_16x16x32_bf16 v[84:87], v[164:167], v[242:245], v[84:87]
	v_mfma_f32_16x16x32_bf16 v[68:71], v[164:167], v[246:249], v[68:71]
	v_mfma_f32_16x16x32_bf16 v[80:83], v[170:173], v[242:245], v[80:83]
	v_mfma_f32_16x16x32_bf16 v[64:67], v[170:173], v[246:249], v[64:67]
	ds_read_b128 v[242:245], v168 offset:12288
	ds_read_b128 v[246:249], v168 offset:14336
	s_waitcnt lgkmcnt(2)
	v_mfma_f32_16x16x32_bf16 v[60:63], v[128:131], v[156:159], v[60:63]
	v_mfma_f32_16x16x32_bf16 v[44:47], v[128:131], v[250:253], v[44:47]
	v_mfma_f32_16x16x32_bf16 v[56:59], v[160:163], v[156:159], v[56:59]
	v_mfma_f32_16x16x32_bf16 v[40:43], v[160:163], v[250:253], v[40:43]
	v_mfma_f32_16x16x32_bf16 v[52:55], v[164:167], v[156:159], v[52:55]
	v_mfma_f32_16x16x32_bf16 v[36:39], v[164:167], v[250:253], v[36:39]
	v_mfma_f32_16x16x32_bf16 v[48:51], v[170:173], v[156:159], v[48:51]
	v_mfma_f32_16x16x32_bf16 v[32:35], v[170:173], v[250:253], v[32:35]
	s_cbranch_scc0 .Lg2l_gemm3
	s_waitcnt vmcnt(0) lgkmcnt(0)
	s_branch .Lg2j_gemm3

.LBB0_1531:
	v_readfirstlane_b32 s12, v146
	s_xor_b32 m0, s25, 1
	s_lshl_b32 m0, m0, 16
	s_add_i32 s12, s12, m0
	v_add3_u32 v128, s24, v147, v148
	v_add_u32_e32 v172, v128, v150
	v_add3_u32 v176, s24, v149, v148
	v_add_u32_e32 v177, v176, v150
	ds_read_b128 v[152:155], v172 offset:32768
	ds_read_b128 v[156:159], v172 offset:34816
	ds_read_b128 v[168:171], v172 offset:36864
	ds_read_b128 v[172:175], v172 offset:38912
	ds_read_b128 v[160:163], v177
	ds_read_b128 v[164:167], v177 offset:2048
	ds_read_b128 v[242:245], v177 offset:4096
	ds_read_b128 v[246:249], v177 offset:6144
	s_mov_b32 m0, s12
	v_lshl_add_u64 v[254:255], v[130:131], 0, s[10:11]
	global_load_lds_dwordx4 v[254:255], off
	s_add_i32 m0, s12, 0x2000
	v_lshl_add_u64 v[254:255], v[132:133], 0, s[10:11]
	global_load_lds_dwordx4 v[254:255], off
	s_waitcnt lgkmcnt(2)
	v_mfma_f32_16x16x32_bf16 v[124:127], v[152:155], v[160:163], v[124:127]
	v_add_u32_e32 v128, v128, v151
	v_add_u32_e32 v176, v176, v151
	v_mfma_f32_16x16x32_bf16 v[108:111], v[152:155], v[164:167], v[108:111]
	v_mfma_f32_16x16x32_bf16 v[120:123], v[156:159], v[160:163], v[120:123]
	v_mfma_f32_16x16x32_bf16 v[104:107], v[156:159], v[164:167], v[104:107]
	s_add_i32 m0, s12, 0x4000
	v_lshl_add_u64 v[254:255], v[134:135], 0, s[10:11]
	global_load_lds_dwordx4 v[254:255], off
	v_mfma_f32_16x16x32_bf16 v[116:119], v[168:171], v[160:163], v[116:119]
	v_mfma_f32_16x16x32_bf16 v[100:103], v[168:171], v[164:167], v[100:103]
	v_mfma_f32_16x16x32_bf16 v[112:115], v[172:175], v[160:163], v[112:115]
	v_mfma_f32_16x16x32_bf16 v[96:99], v[172:175], v[164:167], v[96:99]
	s_add_i32 m0, s12, 0x6000
	v_lshl_add_u64 v[254:255], v[136:137], 0, s[10:11]
	global_load_lds_dwordx4 v[254:255], off
	ds_read_b128 v[160:163], v177 offset:8192
	ds_read_b128 v[164:167], v177 offset:10240
	s_waitcnt lgkmcnt(2)
	v_mfma_f32_16x16x32_bf16 v[92:95], v[152:155], v[242:245], v[92:95]
	v_mfma_f32_16x16x32_bf16 v[76:79], v[152:155], v[246:249], v[76:79]
	v_mfma_f32_16x16x32_bf16 v[88:91], v[156:159], v[242:245], v[88:91]
	v_mfma_f32_16x16x32_bf16 v[72:75], v[156:159], v[246:249], v[72:75]
	s_add_i32 m0, s12, 0x8000
	v_lshl_add_u64 v[254:255], v[138:139], 0, s[10:11]
	global_load_lds_dwordx4 v[254:255], off
	v_mfma_f32_16x16x32_bf16 v[84:87], v[168:171], v[242:245], v[84:87]
	v_mfma_f32_16x16x32_bf16 v[68:71], v[168:171], v[246:249], v[68:71]
	v_mfma_f32_16x16x32_bf16 v[80:83], v[172:175], v[242:245], v[80:83]
	v_mfma_f32_16x16x32_bf16 v[64:67], v[172:175], v[246:249], v[64:67]
	s_add_i32 m0, s12, 0xa000
	v_lshl_add_u64 v[254:255], v[140:141], 0, s[10:11]
	global_load_lds_dwordx4 v[254:255], off
	ds_read_b128 v[242:245], v177 offset:12288
	ds_read_b128 v[246:249], v177 offset:14336
	s_waitcnt lgkmcnt(2)
	v_mfma_f32_16x16x32_bf16 v[60:63], v[152:155], v[160:163], v[60:63]
	v_mfma_f32_16x16x32_bf16 v[44:47], v[152:155], v[164:167], v[44:47]
	v_mfma_f32_16x16x32_bf16 v[56:59], v[156:159], v[160:163], v[56:59]
	v_mfma_f32_16x16x32_bf16 v[40:43], v[156:159], v[164:167], v[40:43]
	s_add_i32 m0, s12, 0xc000
	v_lshl_add_u64 v[254:255], v[142:143], 0, s[10:11]
	global_load_lds_dwordx4 v[254:255], off
	v_mfma_f32_16x16x32_bf16 v[52:55], v[168:171], v[160:163], v[52:55]
	v_mfma_f32_16x16x32_bf16 v[36:39], v[168:171], v[164:167], v[36:39]
	v_mfma_f32_16x16x32_bf16 v[48:51], v[172:175], v[160:163], v[48:51]
	v_mfma_f32_16x16x32_bf16 v[32:35], v[172:175], v[164:167], v[32:35]
	s_add_i32 m0, s12, 0xe000
	v_lshl_add_u64 v[254:255], v[144:145], 0, s[10:11]
	global_load_lds_dwordx4 v[254:255], off
	s_add_u32 s10, s10, 0x80
	s_addc_u32 s11, s11, 0
	s_add_i32 s9, s9, 1
	s_cmpk_lg_i32 s10, 0x800
	ds_read_b128 v[160:163], v176
	ds_read_b128 v[164:167], v176 offset:2048
	s_waitcnt lgkmcnt(2)
	v_mfma_f32_16x16x32_bf16 v[28:31], v[152:155], v[242:245], v[28:31]
	v_mfma_f32_16x16x32_bf16 v[8:11], v[152:155], v[246:249], v[8:11]
	ds_read_b128 v[152:155], v128 offset:32768
	v_mfma_f32_16x16x32_bf16 v[24:27], v[156:159], v[242:245], v[24:27]
	v_mfma_f32_16x16x32_bf16 v[4:7], v[156:159], v[246:249], v[4:7]
	ds_read_b128 v[156:159], v128 offset:34816
	v_mfma_f32_16x16x32_bf16 v[16:19], v[168:171], v[242:245], v[16:19]
	v_mfma_f32_16x16x32_bf16 v[0:3], v[168:171], v[246:249], v[0:3]
	ds_read_b128 v[168:171], v128 offset:36864
	v_mfma_f32_16x16x32_bf16 v[12:15], v[172:175], v[242:245], v[12:15]
	v_mfma_f32_16x16x32_bf16 v[20:23], v[172:175], v[246:249], v[20:23]
	ds_read_b128 v[172:175], v128 offset:38912
	ds_read_b128 v[242:245], v176 offset:4096
	ds_read_b128 v[246:249], v176 offset:6144
	s_waitcnt lgkmcnt(2)
	v_mfma_f32_16x16x32_bf16 v[124:127], v[152:155], v[160:163], v[124:127]
	v_mfma_f32_16x16x32_bf16 v[108:111], v[152:155], v[164:167], v[108:111]
	v_mfma_f32_16x16x32_bf16 v[120:123], v[156:159], v[160:163], v[120:123]
	v_mfma_f32_16x16x32_bf16 v[104:107], v[156:159], v[164:167], v[104:107]
	v_mfma_f32_16x16x32_bf16 v[116:119], v[168:171], v[160:163], v[116:119]
	v_mfma_f32_16x16x32_bf16 v[100:103], v[168:171], v[164:167], v[100:103]
	v_mfma_f32_16x16x32_bf16 v[112:115], v[172:175], v[160:163], v[112:115]
	v_mfma_f32_16x16x32_bf16 v[96:99], v[172:175], v[164:167], v[96:99]
	ds_read_b128 v[160:163], v176 offset:8192
	ds_read_b128 v[164:167], v176 offset:10240
	s_waitcnt lgkmcnt(2)
	v_mfma_f32_16x16x32_bf16 v[92:95], v[152:155], v[242:245], v[92:95]
	v_mfma_f32_16x16x32_bf16 v[76:79], v[152:155], v[246:249], v[76:79]
	v_mfma_f32_16x16x32_bf16 v[88:91], v[156:159], v[242:245], v[88:91]
	v_mfma_f32_16x16x32_bf16 v[72:75], v[156:159], v[246:249], v[72:75]
	v_mfma_f32_16x16x32_bf16 v[84:87], v[168:171], v[242:245], v[84:87]
	v_mfma_f32_16x16x32_bf16 v[68:71], v[168:171], v[246:249], v[68:71]
	v_mfma_f32_16x16x32_bf16 v[80:83], v[172:175], v[242:245], v[80:83]
	v_mfma_f32_16x16x32_bf16 v[64:67], v[172:175], v[246:249], v[64:67]
	ds_read_b128 v[242:245], v176 offset:12288
	ds_read_b128 v[246:249], v176 offset:14336
	s_waitcnt lgkmcnt(2)
	v_mfma_f32_16x16x32_bf16 v[60:63], v[152:155], v[160:163], v[60:63]
	v_mfma_f32_16x16x32_bf16 v[44:47], v[152:155], v[164:167], v[44:47]
	v_mfma_f32_16x16x32_bf16 v[56:59], v[156:159], v[160:163], v[56:59]
	v_mfma_f32_16x16x32_bf16 v[40:43], v[156:159], v[164:167], v[40:43]
	v_mfma_f32_16x16x32_bf16 v[52:55], v[168:171], v[160:163], v[52:55]
	v_mfma_f32_16x16x32_bf16 v[36:39], v[168:171], v[164:167], v[36:39]
	v_mfma_f32_16x16x32_bf16 v[48:51], v[172:175], v[160:163], v[48:51]
	v_mfma_f32_16x16x32_bf16 v[32:35], v[172:175], v[164:167], v[32:35]
	s_cbranch_scc0 .Lg2l_gemm0
	s_waitcnt vmcnt(0) lgkmcnt(0)
	s_branch .Lg2j_gemm0

.Lg2j_gemm0:
	v_mfma_f32_16x16x32_bf16 v[28:31], v[152:155], v[242:245], v[28:31]
	s_barrier
	v_mfma_f32_16x16x32_bf16 v[8:11], v[152:155], v[246:249], v[8:11]
	v_mfma_f32_16x16x32_bf16 v[24:27], v[156:159], v[242:245], v[24:27]
	v_mfma_f32_16x16x32_bf16 v[4:7], v[156:159], v[246:249], v[4:7]
	v_mfma_f32_16x16x32_bf16 v[16:19], v[168:171], v[242:245], v[16:19]
	v_mfma_f32_16x16x32_bf16 v[0:3], v[168:171], v[246:249], v[0:3]
	v_mfma_f32_16x16x32_bf16 v[12:15], v[172:175], v[242:245], v[12:15]
	v_mfma_f32_16x16x32_bf16 v[20:23], v[172:175], v[246:249], v[20:23]
	s_cbranch_scc0 .LBB0_1528
